# sample band attention spread over 64 WGs (2 heads per WG) instead of 16
# speedup vs baseline: 1.0021x; 1.0021x over previous
.LBB0_756:
	s_or_b64 exec, exec, s[0:1]
	s_mov_b64 s[38:39], s[62:63]
	s_mov_b64 s[0:1], s[60:61]
	v_mov_b32_e32 v96, v220
	s_waitcnt lgkmcnt(0)
	s_barrier
	s_cmpk_gt_i32 s2, 0x7f
	s_mov_b64 s[8:9], -1
	v_readfirstlane_b32 s22, v96
	s_cbranch_scc0 .LBB0_785
	s_add_u32 s21, s38, 0x7700000
	s_addc_u32 s20, s39, 0
	v_and_b32_e32 v0, 63, v96
	s_cmpk_gt_u32 s2, 0xbf
	s_cbranch_scc0 .LBB0_765
	s_sub_i32 s8, s96, 64
	s_cmp_lt_i32 s2, s8
	s_cbranch_scc1 .LBB0_764
	s_not_b32 s8, s2
	s_add_i32 s42, s96, s8
	s_ashr_i32 s8, s42, 2
	s_ashr_i32 s9, s8, 31
	s_and_b32 s33, s42, 3
	s_lshl_b64 s[40:41], s[8:9], 5
	s_add_u32 s8, s40, 0x8000
	s_addc_u32 s9, s41, 0
	s_ashr_i32 s43, s42, 31
	s_lshl_b32 s50, s33, 6
	s_lshl_b32 s23, s33, 7
	s_lshl_b64 s[10:11], s[42:43], 13
	s_lshl_b64 s[42:43], s[42:43], 15
	s_add_u32 s14, s14, s42
	s_addc_u32 s15, s15, s43
	s_add_u32 s44, s38, 0x16a80000
	s_addc_u32 s45, s39, 0
	s_add_u32 s46, s38, 0x17ac0000
	v_ashrrev_i32_e32 v6, 6, v96
	v_add_u32_e32 v1, 0x200, v96
	v_add_u32_e32 v24, 0x400, v96
	s_addc_u32 s47, s39, 0
	s_lshl_b32 s33, s33, 8
	v_ashrrev_i32_e32 v7, 31, v6
	v_ashrrev_i32_e32 v12, 6, v1
	v_ashrrev_i32_e32 v18, 6, v24
	s_add_u32 s42, s38, s33
	v_lshl_add_u64 v[8:9], s[8:9], 0, v[6:7]
	v_ashrrev_i32_e32 v13, 31, v12
	v_ashrrev_i32_e32 v19, 31, v18
	v_mov_b32_e32 v3, 0
	v_lshlrev_b32_e32 v2, 2, v0
	s_addc_u32 s43, s39, 0
	v_lshlrev_b64 v[8:9], 8, v[8:9]
	v_lshl_add_u64 v[14:15], s[8:9], 0, v[12:13]
	v_lshl_add_u64 v[20:21], s[8:9], 0, v[18:19]
	v_lshl_add_u64 v[4:5], s[42:43], 0, v[2:3]
	s_mov_b64 s[48:49], 0x1ec00000
	v_or3_b32 v8, v8, v0, s50
	v_lshl_add_u64 v[6:7], s[40:41], 0, v[6:7]
	v_lshlrev_b64 v[14:15], 8, v[14:15]
	v_lshlrev_b64 v[20:21], 8, v[20:21]
	v_lshl_add_u64 v[4:5], v[4:5], 0, s[48:49]
	v_lshlrev_b64 v[8:9], 1, v[8:9]
	v_lshlrev_b64 v[6:7], 10, v[6:7]
	v_or3_b32 v14, v14, v0, s50
	v_lshl_add_u64 v[12:13], s[40:41], 0, v[12:13]
	v_or3_b32 v20, v20, v0, s50
	v_lshl_add_u64 v[10:11], s[44:45], 0, v[8:9]
	v_lshl_add_u64 v[6:7], v[4:5], 0, v[6:7]
	v_lshlrev_b64 v[14:15], 1, v[14:15]
	v_lshlrev_b64 v[12:13], 10, v[12:13]
	v_lshlrev_b64 v[20:21], 1, v[20:21]
	v_lshl_add_u64 v[8:9], s[46:47], 0, v[8:9]
	v_lshl_add_u64 v[16:17], s[44:45], 0, v[14:15]
	v_lshl_add_u64 v[14:15], s[46:47], 0, v[14:15]
	v_lshl_add_u64 v[12:13], v[4:5], 0, v[12:13]
	v_lshl_add_u64 v[22:23], s[44:45], 0, v[20:21]
	v_lshl_add_u64 v[20:21], s[46:47], 0, v[20:21]
	global_load_ushort v48, v[10:11], off
	global_load_ushort v49, v[8:9], off
	global_load_dword v50, v[6:7], off
	global_load_ushort v51, v[16:17], off
	global_load_ushort v52, v[14:15], off
	global_load_dword v53, v[12:13], off
	global_load_ushort v54, v[22:23], off
	global_load_ushort v55, v[20:21], off
	v_lshl_add_u64 v[6:7], s[40:41], 0, v[18:19]
	v_add_u32_e32 v18, 0x600, v96
	v_ashrrev_i32_e32 v8, 6, v18
	v_ashrrev_i32_e32 v9, 31, v8
	v_lshl_add_u64 v[10:11], s[8:9], 0, v[8:9]
	v_lshl_add_u64 v[8:9], s[40:41], 0, v[8:9]
	v_and_b32_e32 v56, 0x7f, v96
	v_ashrrev_i32_e32 v38, 7, v96
	v_ashrrev_i32_e32 v14, 7, v1
	v_ashrrev_i32_e32 v16, 7, v24
	v_ashrrev_i32_e32 v18, 7, v18
	v_lshlrev_b64 v[6:7], 10, v[6:7]
	v_lshlrev_b64 v[10:11], 8, v[10:11]
	v_lshlrev_b64 v[8:9], 10, v[8:9]
	v_lshlrev_b32_e32 v2, 1, v56
	v_ashrrev_i32_e32 v39, 31, v38
	v_ashrrev_i32_e32 v15, 31, v14
	v_ashrrev_i32_e32 v17, 31, v16
	v_ashrrev_i32_e32 v19, 31, v18
	v_lshl_add_u64 v[6:7], v[4:5], 0, v[6:7]
	v_or3_b32 v10, v10, v0, s50
	v_lshl_add_u64 v[4:5], v[4:5], 0, v[8:9]
	v_lshl_add_u64 v[2:3], s[42:43], 0, v[2:3]
	s_mov_b64 s[42:43], 0x1ab00000
	v_lshl_add_u64 v[8:9], s[40:41], 0, v[38:39]
	v_lshl_add_u64 v[14:15], s[40:41], 0, v[14:15]
	v_lshl_add_u64 v[16:17], s[40:41], 0, v[16:17]
	v_lshl_add_u64 v[18:19], s[40:41], 0, v[18:19]
	v_lshlrev_b64 v[10:11], 1, v[10:11]
	v_lshl_add_u64 v[2:3], v[2:3], 0, s[42:43]
	v_lshlrev_b64 v[8:9], 10, v[8:9]
	v_lshlrev_b64 v[14:15], 10, v[14:15]
	v_lshlrev_b64 v[16:17], 10, v[16:17]
	v_lshlrev_b64 v[18:19], 10, v[18:19]
	v_add_u32_e32 v1, 0x800, v96
	v_lshl_add_u64 v[12:13], s[44:45], 0, v[10:11]
	v_lshl_add_u64 v[10:11], s[46:47], 0, v[10:11]
	v_lshl_add_u64 v[8:9], v[2:3], 0, v[8:9]
	v_lshl_add_u64 v[14:15], v[2:3], 0, v[14:15]
	v_lshl_add_u64 v[16:17], v[2:3], 0, v[16:17]
	v_lshl_add_u64 v[18:19], v[2:3], 0, v[18:19]
	global_load_dword v39, v[6:7], off
	global_load_ushort v57, v[12:13], off
	global_load_ushort v58, v[10:11], off
	global_load_dword v59, v[4:5], off
	global_load_ushort v60, v[8:9], off
	global_load_ushort v61, v[14:15], off
	global_load_ushort v62, v[16:17], off
	global_load_ushort v63, v[18:19], off
	v_ashrrev_i32_e32 v4, 7, v1
	v_add_u32_e32 v1, 0xa00, v96
	v_ashrrev_i32_e32 v6, 7, v1
	v_add_u32_e32 v1, 0xc00, v96
	v_ashrrev_i32_e32 v8, 7, v1
	v_add_u32_e32 v1, 0xe00, v96
	v_ashrrev_i32_e32 v10, 7, v1
	v_ashrrev_i32_e32 v5, 31, v4
	v_ashrrev_i32_e32 v7, 31, v6
	v_ashrrev_i32_e32 v9, 31, v8
	v_ashrrev_i32_e32 v11, 31, v10
	v_lshl_add_u64 v[4:5], s[40:41], 0, v[4:5]
	v_lshl_add_u64 v[6:7], s[40:41], 0, v[6:7]
	v_lshl_add_u64 v[8:9], s[40:41], 0, v[8:9]
	v_lshl_add_u64 v[10:11], s[40:41], 0, v[10:11]
	v_lshlrev_b64 v[4:5], 10, v[4:5]
	v_lshlrev_b64 v[6:7], 10, v[6:7]
	v_lshlrev_b64 v[8:9], 10, v[8:9]
	v_lshlrev_b64 v[10:11], 10, v[10:11]
	v_lshl_or_b32 v24, v38, 11, v56
	v_lshl_add_u64 v[4:5], v[2:3], 0, v[4:5]
	v_lshl_add_u64 v[6:7], v[2:3], 0, v[6:7]
	v_lshl_add_u64 v[8:9], v[2:3], 0, v[8:9]
	v_lshl_add_u64 v[2:3], v[2:3], 0, v[10:11]
	v_ashrrev_i32_e32 v25, 31, v24
	global_load_ushort v64, v[4:5], off
	global_load_ushort v65, v[6:7], off
	global_load_ushort v66, v[8:9], off
	global_load_ushort v67, v[2:3], off
	v_lshl_add_u64 v[2:3], v[24:25], 2, s[14:15]
	global_load_dword v32, v[2:3], off
	global_load_dword v33, v[2:3], off offset:512
	global_load_dword v30, v[2:3], off offset:1024
	global_load_dword v31, v[2:3], off offset:1536
	global_load_dword v28, v[2:3], off offset:2048
	global_load_dword v29, v[2:3], off offset:2560
	global_load_dword v26, v[2:3], off offset:3072
	global_load_dword v27, v[2:3], off offset:3584
	v_or_b32_e32 v34, 0x400, v24
	v_or_b32_e32 v2, 0x480, v24
	v_or_b32_e32 v4, 0x500, v24
	v_or_b32_e32 v6, 0x580, v24
	v_ashrrev_i32_e32 v35, 31, v34
	v_ashrrev_i32_e32 v3, 31, v2
	v_ashrrev_i32_e32 v5, 31, v4
	v_ashrrev_i32_e32 v7, 31, v6
	v_or_b32_e32 v8, 0x600, v24
	v_or_b32_e32 v10, 0x680, v24
	v_or_b32_e32 v12, 0x700, v24
	v_or_b32_e32 v14, 0x780, v24
	v_lshl_add_u64 v[16:17], v[34:35], 2, s[14:15]
	v_lshl_add_u64 v[18:19], v[2:3], 2, s[14:15]
	v_lshl_add_u64 v[22:23], v[4:5], 2, s[14:15]
	v_lshl_add_u64 v[36:37], v[6:7], 2, s[14:15]
	v_ashrrev_i32_e32 v9, 31, v8
	v_ashrrev_i32_e32 v11, 31, v10
	v_ashrrev_i32_e32 v13, 31, v12
	v_ashrrev_i32_e32 v15, 31, v14
	v_lshl_add_u64 v[40:41], v[8:9], 2, s[14:15]
	v_lshl_add_u64 v[42:43], v[10:11], 2, s[14:15]
	v_lshl_add_u64 v[44:45], v[12:13], 2, s[14:15]
	v_lshl_add_u64 v[46:47], v[14:15], 2, s[14:15]
	global_load_dword v20, v[16:17], off
	global_load_dword v21, v[18:19], off
	s_nop 0
	global_load_dword v18, v[22:23], off
	global_load_dword v19, v[36:37], off
	global_load_dword v16, v[40:41], off
	global_load_dword v17, v[42:43], off
	s_nop 0
	global_load_dword v22, v[44:45], off
	global_load_dword v36, v[46:47], off
	s_waitcnt vmcnt(33)
	v_mul_f32_e32 v40, 0x3fb8aa3b, v50
	s_waitcnt vmcnt(30)
	v_mul_f32_e32 v42, 0x3fb8aa3b, v53
	v_lshlrev_b32_e32 v23, 16, v48
	v_lshl_add_u32 v1, v96, 2, 0
	v_exp_f32_e32 v40, v40
	v_lshlrev_b32_e32 v41, 16, v51
	v_exp_f32_e32 v42, v42
	ds_write2st64_b32 v1, v23, v41 offset1:8
	v_lshlrev_b32_e32 v37, 16, v49
	v_lshlrev_b32_e32 v23, 16, v52
	ds_write2st64_b32 v1, v37, v23 offset0:32 offset1:40
	ds_write2st64_b32 v1, v40, v42 offset0:64 offset1:72
	s_waitcnt vmcnt(29)
	v_lshlrev_b32_e32 v23, 16, v54
	s_waitcnt vmcnt(28)
	v_lshlrev_b32_e32 v37, 16, v55
	s_movk_i32 s14, 0x80
	s_mov_b32 s33, 0
	v_cmp_gt_i32_e32 vcc, s14, v96
	v_lshl_add_u32 v38, v38, 6, 0
	s_waitcnt vmcnt(27)
	v_mul_f32_e32 v39, 0x3fb8aa3b, v39
	v_exp_f32_e32 v39, v39
	s_waitcnt vmcnt(26)
	v_lshlrev_b32_e32 v40, 16, v57
	s_waitcnt vmcnt(24)
	v_mul_f32_e32 v41, 0x3fb8aa3b, v59
	v_exp_f32_e32 v41, v41
	ds_write2st64_b32 v1, v23, v40 offset0:16 offset1:24
	v_lshlrev_b32_e32 v23, 16, v58
	ds_write2st64_b32 v1, v37, v23 offset0:48 offset1:56
	ds_write2st64_b32 v1, v39, v41 offset0:80 offset1:88
	s_waitcnt vmcnt(23)
	v_lshlrev_b32_e32 v23, 16, v60
	s_waitcnt vmcnt(22)
	v_lshlrev_b32_e32 v37, 16, v61
	ds_write2st64_b32 v1, v23, v37 offset0:96 offset1:104
	s_waitcnt vmcnt(21)
	v_lshlrev_b32_e32 v23, 16, v62
	s_waitcnt vmcnt(20)
	v_lshlrev_b32_e32 v37, 16, v63
	ds_write2st64_b32 v1, v23, v37 offset0:112 offset1:120
	v_add_u32_e32 v39, 0xa800, v1
	s_waitcnt vmcnt(19)
	v_lshlrev_b32_e32 v23, 16, v64
	s_waitcnt vmcnt(18)
	v_lshlrev_b32_e32 v37, 16, v65
	ds_write2st64_b32 v1, v23, v37 offset0:128 offset1:136
	s_waitcnt vmcnt(17)
	v_lshlrev_b32_e32 v23, 16, v66
	s_waitcnt vmcnt(16)
	v_lshlrev_b32_e32 v37, 16, v67
	ds_write2st64_b32 v1, v23, v37 offset0:144 offset1:152
	v_lshl_add_u32 v23, v56, 2, 0
	v_add_u32_e32 v40, 0x6000, v23
	s_waitcnt lgkmcnt(0)
	s_barrier
	s_branch .LBB0_761

.LBB0_778:
	s_or_b64 exec, exec, s[8:9]
	s_cmp_gt_u32 s22, 0x7f
	s_cbranch_scc0 .Lsa_active
	s_waitcnt lgkmcnt(0)
	s_barrier
	s_branch .LBB0_784
.Lsa_active:
	s_and_b32 s98, s2, 3
	s_lshl_b32 s98, s98, 7
	s_add_i32 s22, s22, s98
	s_add_i32 s10, s2, 0xffffff80
	s_lshr_b32 s10, s10, 2
	s_lshl_b32 s8, s10, 5
	s_mov_b32 s11, 0
	s_add_i32 s8, s8, 0x8000
	s_mov_b32 s9, s11
	s_lshl_b64 s[14:15], s[8:9], 10
	s_mul_hi_u32 s33, s10, 0x88000
	s_mul_i32 s40, s10, 0x88000
	s_lshl_b32 s10, s10, 3
	s_ashr_i32 s44, s22, 6
	s_add_u32 s23, s38, s14
	s_addc_u32 s41, s39, s15
	s_and_b32 s14, s22, 0xffffffc0
	s_ashr_i32 s15, s14, 31
	s_lshl_b64 s[14:15], s[14:15], 1
	s_add_u32 s22, s23, s14
	s_addc_u32 s23, s41, s15
	s_add_u32 s40, s38, s40
	s_addc_u32 s33, s39, s33
	s_add_u32 s40, s40, s14
	v_and_b32_e32 v104, 31, v96
	s_addc_u32 s41, s33, s15
	s_add_i32 s10, s44, s10
	v_lshrrev_b32_e32 v97, 5, v0
	v_lshlrev_b32_e32 v98, 10, v104
	v_mov_b32_e32 v99, 0
	s_mul_hi_i32 s33, s10, 0x11000
	s_mul_i32 s10, s10, 0x11000
	v_lshl_add_u64 v[2:3], s[22:23], 0, v[98:99]
	v_lshlrev_b32_e32 v98, 4, v97
	s_add_u32 s42, s38, s10
	v_lshl_add_u64 v[2:3], v[2:3], 0, v[98:99]
	s_mov_b64 s[22:23], 0xf900000
	s_mov_b32 s10, 0xf900000
	v_lshl_add_u64 v[4:5], v[2:3], 0, s[22:23]
	v_add_co_u32_e32 v2, vcc, s10, v2
	v_lshlrev_b32_e32 v6, 4, v96
	s_nop 0
	v_addc_co_u32_e32 v3, vcc, 0, v3, vcc
	s_waitcnt lgkmcnt(0)
	s_barrier
	global_load_dwordx4 v[48:51], v[4:5], off offset:32
	global_load_dwordx4 v[52:55], v[4:5], off offset:64
	global_load_dwordx4 v[56:59], v[2:3], off
	global_load_dwordx4 v[60:63], v[4:5], off offset:96
	v_and_b32_e32 v2, 0x70, v6
	v_mov_b32_e32 v3, v99
	v_lshrrev_b32_e32 v1, 2, v0
	v_lshl_add_u64 v[4:5], s[40:41], 0, v[2:3]
	s_mov_b64 s[22:23], 0x15980000
	s_addc_u32 s43, s39, s33
	v_lshl_add_u64 v[100:101], v[4:5], 0, s[22:23]
	v_and_b32_e32 v4, 48, v6
	v_mov_b32_e32 v5, v99
	v_mul_u32_u24_e32 v3, 0x220, v1
	v_lshl_add_u64 v[6:7], s[42:43], 0, v[4:5]
	v_lshlrev_b32_e32 v10, 1, v3
	v_mov_b32_e32 v11, v99
	v_lshrrev_b32_e32 v105, 3, v0
	v_lshl_add_u64 v[6:7], v[6:7], 0, v[10:11]
	s_mov_b32 s10, 0x16200000
	v_lshlrev_b32_e32 v8, 10, v105
	v_mov_b32_e32 v9, v99
	v_add_co_u32_e32 v10, vcc, s10, v6
	v_lshl_add_u64 v[8:9], v[100:101], 0, v[8:9]
	s_nop 0
	v_addc_co_u32_e32 v11, vcc, 0, v7, vcc
	s_movk_i32 s22, 0x2000
	global_load_dwordx4 v[64:67], v[8:9], off
	global_load_dwordx4 v[68:71], v[10:11], off
	v_add_co_u32_e32 v10, vcc, s22, v8
	s_mov_b32 s10, 0x16204000
	s_nop 0
	v_addc_co_u32_e32 v11, vcc, 0, v9, vcc
	v_add_co_u32_e32 v12, vcc, s10, v6
	s_movk_i32 s23, 0x4000
	s_nop 0
	v_addc_co_u32_e32 v13, vcc, 0, v7, vcc
	global_load_dwordx4 v[72:75], v[10:11], off
	global_load_dwordx4 v[76:79], v[12:13], off offset:1024
	v_add_co_u32_e32 v10, vcc, s23, v8
	s_mov_b32 s10, 0x16208000
	s_nop 0
	v_addc_co_u32_e32 v11, vcc, 0, v9, vcc
	v_add_co_u32_e32 v12, vcc, s10, v6
	s_movk_i32 s33, 0x6000
	s_nop 0
	v_addc_co_u32_e32 v13, vcc, 0, v7, vcc
	v_add_co_u32_e32 v8, vcc, s33, v8
	s_mov_b32 s10, 0x1620c000
	s_nop 0
	v_addc_co_u32_e32 v9, vcc, 0, v9, vcc
	global_load_dwordx4 v[80:83], v[10:11], off
	global_load_dwordx4 v[84:87], v[12:13], off offset:2048
	v_add_co_u32_e32 v10, vcc, s10, v6
	s_mul_i32 s10, s44, 0xa00
	s_nop 0
	v_addc_co_u32_e32 v11, vcc, 0, v7, vcc
	global_load_dwordx4 v[88:91], v[8:9], off
	global_load_dwordx4 v[92:95], v[10:11], off offset:3072
	s_add_i32 s40, s10, 0
	s_mulk_i32 s44, 0x1c00
	s_add_i32 s42, s40, s44
	s_mov_b64 s[40:41], 0x16200000
	v_lshl_add_u64 v[102:103], v[6:7], 0, s[40:41]
	v_add_u32_e32 v32, s42, v2
	s_movk_i32 s40, 0x90
	v_mov_b32_e32 v2, s42
	v_mad_u32_u24 v34, v104, s40, v2
	v_mbcnt_hi_u32_b32 v2, -1, v221
	v_add_u32_e32 v33, s42, v4
	v_and_b32_e32 v4, 64, v2
	v_or_b32_e32 v0, 32, v0
	v_xor_b32_e32 v3, 32, v2
	v_add_u32_e32 v4, 64, v4
	v_mul_u32_u24_e32 v37, 0x50, v1
	v_mul_u32_u24_e32 v39, 0x50, v0
	v_or_b32_e32 v0, s10, v98
	v_lshlrev_b32_e32 v1, 2, v104
	v_cmp_lt_i32_e32 vcc, v3, v4
	v_sub_u32_e32 v0, v0, v1
	v_lshl_add_u32 v35, v97, 3, s42
	v_cndmask_b32_e32 v2, v2, v3, vcc
	v_mul_u32_u24_e32 v36, 0x90, v105
	v_mul_u32_u24_e32 v38, 0x50, v104
	v_add_u32_e32 v0, 0, v0
	v_lshlrev_b32_e32 v106, 2, v2
	v_add_u32_e32 v107, 0x100, v0
	v_mov_b32_e32 v16, v99
	v_mov_b32_e32 v17, v99
	v_mov_b32_e32 v18, v99
	v_mov_b32_e32 v19, v99
	v_mov_b32_e32 v20, v99
	v_mov_b32_e32 v21, v99
	v_mov_b32_e32 v22, v99
	v_mov_b32_e32 v23, v99
	v_mov_b32_e32 v24, v99
	v_mov_b32_e32 v25, v99
	v_mov_b32_e32 v26, v99
	v_mov_b32_e32 v27, v99
	v_mov_b32_e32 v28, v99
	v_mov_b32_e32 v29, v99
	v_mov_b32_e32 v30, v99
	v_mov_b32_e32 v31, v99
	v_mov_b32_e32 v0, v99
	v_mov_b32_e32 v1, v99
	v_mov_b32_e32 v2, v99
	v_mov_b32_e32 v3, v99
	v_mov_b32_e32 v4, v99
	v_mov_b32_e32 v6, v99
	v_mov_b32_e32 v7, v99
	v_mov_b32_e32 v8, v99
	v_mov_b32_e32 v9, v99
	v_mov_b32_e32 v10, v99
	v_mov_b32_e32 v11, v99
	v_mov_b32_e32 v12, v99
	v_mov_b32_e32 v13, v99
	v_mov_b32_e32 v14, v99
	v_mov_b32_e32 v15, v99
	v_mov_b32_e32 v110, 0xff800000
	v_add_u32_e32 v108, v32, v36
	v_add_u32_e32 v109, v33, v37
	v_add_u32_e32 v111, v34, v98
	v_add_u32_e32 v112, v35, v38
	v_add_u32_e32 v113, v35, v39
	v_mov_b32_e32 v114, 0
	s_mov_b32 s42, 0

	.amdhsa_kernel _Z14fwd_megakernel6Params
		.amdhsa_group_segment_fixed_size 0
		.amdhsa_private_segment_fixed_size 0
		.amdhsa_kernarg_size 496
		.amdhsa_user_sgpr_count 2
		.amdhsa_user_sgpr_dispatch_ptr 0
		.amdhsa_user_sgpr_queue_ptr 0
		.amdhsa_user_sgpr_kernarg_segment_ptr 1
		.amdhsa_user_sgpr_dispatch_id 0
		.amdhsa_user_sgpr_kernarg_preload_length 0
		.amdhsa_user_sgpr_kernarg_preload_offset 0
		.amdhsa_user_sgpr_private_segment_size 0
		.amdhsa_uses_dynamic_stack 0
		.amdhsa_enable_private_segment 0
		.amdhsa_system_sgpr_workgroup_id_x 1
		.amdhsa_system_sgpr_workgroup_id_y 0
		.amdhsa_system_sgpr_workgroup_id_z 0
		.amdhsa_system_sgpr_workgroup_info 0
		.amdhsa_system_vgpr_workitem_id 2
		.amdhsa_next_free_vgpr 246
		.amdhsa_next_free_sgpr 102
		.amdhsa_accum_offset 248
		.amdhsa_reserve_vcc 1
		.amdhsa_float_round_mode_32 0
		.amdhsa_float_round_mode_16_64 0
		.amdhsa_float_denorm_mode_32 3
		.amdhsa_float_denorm_mode_16_64 3
		.amdhsa_dx10_clamp 1
		.amdhsa_ieee_mode 1
		.amdhsa_fp16_overflow 0
		.amdhsa_tg_split 0
		.amdhsa_exception_fp_ieee_invalid_op 0
		.amdhsa_exception_fp_denorm_src 0
		.amdhsa_exception_fp_ieee_div_zero 0
		.amdhsa_exception_fp_ieee_overflow 0
		.amdhsa_exception_fp_ieee_underflow 0
		.amdhsa_exception_fp_ieee_inexact 0
		.amdhsa_exception_int_div_zero 0
	.end_amdhsa_kernel

amdhsa.kernels:
  - .agpr_count:     0
    .args:
      - .offset:         0
        .size:           240
        .value_kind:     by_value
      - .offset:         240
        .size:           4
        .value_kind:     hidden_block_count_x
      - .offset:         244
        .size:           4
        .value_kind:     hidden_block_count_y
      - .offset:         248
        .size:           4
        .value_kind:     hidden_block_count_z
      - .offset:         252
        .size:           2
        .value_kind:     hidden_group_size_x
      - .offset:         254
        .size:           2
        .value_kind:     hidden_group_size_y
      - .offset:         256
        .size:           2
        .value_kind:     hidden_group_size_z
      - .offset:         258
        .size:           2
        .value_kind:     hidden_remainder_x
      - .offset:         260
        .size:           2
        .value_kind:     hidden_remainder_y
      - .offset:         262
        .size:           2
        .value_kind:     hidden_remainder_z
      - .offset:         280
        .size:           8
        .value_kind:     hidden_global_offset_x
      - .offset:         288
        .size:           8
        .value_kind:     hidden_global_offset_y
      - .offset:         296
        .size:           8
        .value_kind:     hidden_global_offset_z
      - .offset:         304
        .size:           2
        .value_kind:     hidden_grid_dims
      - .offset:         328
        .size:           8
        .value_kind:     hidden_multigrid_sync_arg
      - .offset:         360
        .size:           4
        .value_kind:     hidden_dynamic_lds_size
    .group_segment_fixed_size: 0
    .kernarg_segment_align: 8
    .kernarg_segment_size: 496
    .language:       OpenCL C
    .language_version:
      - 2
      - 0
    .max_flat_workgroup_size: 512
    .name:           _Z14fwd_megakernel6Params
    .private_segment_fixed_size: 0
    .sgpr_count:     108
    .sgpr_spill_count: 125
    .symbol:         _Z14fwd_megakernel6Params.kd
    .uniform_work_group_size: 1
    .uses_dynamic_stack: false
    .vgpr_count:     246
    .vgpr_spill_count: 0
    .wavefront_size: 64
